# barrier-word init wait and arrival post deferred from kernel entry to the end of P0 so the other 255 workgroups start P0 immediately
# baseline (speedup 1.0000x reference)
; __global__ void __launch_bounds__(512, 2) fwd_megakernel(Params p) {
;     ...
;     {
;         unsigned* flag = barw + 16384 - 64;
;         constexpr unsigned MAGIC = 0x600DF1A6u;
;         if (blockIdx.x == 0) {
;             for (int i = threadIdx.x; i < 16384 - 64; i += 512) barw[i] = 0u;
;             __threadfence(); __syncthreads();
;             if (threadIdx.x == 0) { asm volatile("s_waitcnt vmcnt(0)" ::: "memory"); __hip_atomic_store(flag, MAGIC, __ATOMIC_RELEASE, __HIP_MEMORY_SCOPE_AGENT); }
;         } else if (threadIdx.x == 0) {
;             unsigned sp = 0; while (__hip_atomic_load(flag, __ATOMIC_RELAXED, __HIP_MEMORY_SCOPE_AGENT) != MAGIC) { __builtin_amdgcn_s_sleep(1); if (++sp > (1u << 22)) break; }
;             __builtin_amdgcn_fence(__ATOMIC_ACQUIRE, "agent");
;         }
;         __syncthreads();
;     }
.LBB0_14:
	s_add_u32 s96, s72, 0x580000
	s_addc_u32 s97, s73, 0
	s_add_u32 s26, s72, 0x58ff00
	s_addc_u32 s27, s73, 0
	s_cmp_lg_u32 s86, 0
	v_cmp_eq_u32_e32 vcc, 0, v152
	s_cbranch_scc0 .LBB0_24
	s_branch .LBB0_35
.LBB0_24:
	s_branch .LBB0_27
.LBB0_27:
	v_sub_u32_e32 v0, 0x3fbf, v152
	v_lshrrev_b32_e32 v0, 9, v0
	v_add_u32_e32 v5, 1, v0
	v_and_b32_e32 v4, 62, v5
	v_add_u32_e32 v153, 0x200, v152
	s_mov_b64 s[4:5], 0
	v_mov_b32_e32 v1, 0
	v_mov_b32_e32 v6, v4
	v_mov_b64_e32 v[2:3], v[152:153]

; #define LAS __attribute__((address_space(3)))
; __device__ __forceinline__ unsigned xb_add(unsigned* p, unsigned v) { return __hip_atomic_fetch_add(p, v, __ATOMIC_RELAXED, __HIP_MEMORY_SCOPE_AGENT); }
; __device__ __forceinline__ unsigned xb_xcc_id() { return (unsigned)__builtin_amdgcn_s_getreg((3 << 11) | 20) & 0xFu; }
; __device__ __forceinline__ void p0_prologue(const Params& p, LAS unsigned char* lds, int G) {
;     const int tid = threadIdx.x, lane = tid & 63, wave = __builtin_amdgcn_readfirstlane(tid >> 6);
;     LAS float* scr = (LAS float*)(lds + wave * 8448);
;     const int gw = blockIdx.x * 8 + wave, NGW = G * 8;
;     cvt_gu(p, 0, scr, lane, gw, NGW);
; __device__ __forceinline__ XcdBarrier xcd_barrier_post(unsigned* bar, volatile LAS unsigned* st) {
;     XcdBarrier b; b.bar = bar; b.x = xb_xcc_id(); b.st = st;
;     if (threadIdx.x == 0) (void)xb_add(&bar[XB_XCNT(b.x)], 1u);
;     return b;
; }
.LBB0_38:
	v_readfirstlane_b32 s2, v152
	s_lshr_b32 s33, s2, 6
	s_mul_i32 s2, s33, 0x2100
	s_lshl_b32 s92, s86, 3
	s_add_i32 s3, s2, 0
	s_add_i32 s2, s33, s92
	s_lshl_b32 s4, s74, 3
	s_add_u32 s24, s72, 0x600000
	v_and_b32_e32 v153, 63, v152
	s_addc_u32 s25, s73, 0
	s_add_i32 s6, s2, s4
	v_writelane_b32 v255, s4, 4
	s_cmpk_gt_i32 s6, 0xaff
	v_lshrrev_b32_e32 v173, 5, v153
	v_and_b32_e32 v154, 31, v152
	v_lshlrev_b32_e32 v230, 3, v152
	v_lshrrev_b32_e32 v155, 3, v153
	s_mov_b32 s4, s2
	s_cbranch_scc1 .LBB0_46
	s_cmp_lg_u64 s[10:11], 0
	v_and_b32_e32 v0, 56, v230
	s_cselect_b64 s[4:5], -1, 0
	v_mul_u32_u24_e32 v3, 0x84, v0
	v_lshlrev_b32_e32 v4, 2, v155
	v_mov_b32_e32 v17, 0
	v_lshlrev_b32_e32 v16, 2, v0
	v_lshl_add_u32 v1, v154, 2, s3
	v_mul_u32_u24_e32 v2, 0x84, v173
	v_add3_u32 v29, s3, v3, v4
	v_readlane_b32 s7, v255, 4
	v_cndmask_b32_e64 v3, 0, 1, s[4:5]
	v_lshl_add_u64 v[18:19], s[10:11], 0, v[16:17]
	v_or_b32_e32 v26, 8, v155
	v_or_b32_e32 v27, 16, v155
	v_or_b32_e32 v28, 24, v155
	s_lshl_b32 s36, s74, 4
	s_add_i32 s37, s92, s7
	s_movk_i32 s38, 0x2c00
	v_lshlrev_b32_e32 v16, 2, v154
	s_movk_i32 s39, 0x5000
	s_mov_b32 s40, 0xb000
	s_mov_b32 s41, 0x10000
	s_mov_b32 s42, 0x16000
	s_mov_b32 s43, 0x1b000
	s_mov_b32 s44, 0x21000
	s_mov_b32 s45, 0x26000
	s_mov_b32 s46, 0x2c000
	s_mov_b32 s47, 0x31000
	s_mov_b32 s48, 0x37000
	s_mov_b32 s49, 0x3c000
	s_mov_b32 s50, 0x42000
	s_mov_b32 s51, 0x47000
	s_mov_b32 s52, 0x4d000
	s_mov_b32 s53, 0x52000
	s_mov_b32 s54, 0x58000
	s_mov_b32 s55, 0x5d000
	s_mov_b32 s56, 0x63000
	s_mov_b32 s57, 0x68000
	s_mov_b32 s58, 0x6e000
	s_mov_b32 s59, 0x73000
	s_mov_b32 s60, 0x79000
	s_mov_b32 s61, 0x7e000
	s_mov_b32 s62, 0x84000
	s_mov_b32 s63, 0x89000
	s_mov_b32 s76, 0x8f000
	s_mov_b32 s77, 0x94000
	s_mov_b32 s78, 0x9a000
	v_add_u32_e32 v30, v1, v2
	s_movk_i32 s79, 0x7fff
	s_mov_b32 s80, 0xffff0000
	v_lshlrev_b32_e32 v20, 1, v0
	v_cmp_ne_u32_e64 s[4:5], 1, v3
	s_mov_b32 s81, s2
	s_branch .LBB0_41

; __global__ void __launch_bounds__(512, 2) fwd_megakernel(Params p) {
;     ...
;         unsigned* flag = barw + 16384 - 64;
;         constexpr unsigned MAGIC = 0x600DF1A6u;
;         if (blockIdx.x == 0) {
;             for (int i = threadIdx.x; i < 16384 - 64; i += 512) barw[i] = 0u;
;             __threadfence(); __syncthreads();
;             if (threadIdx.x == 0) { asm volatile("s_waitcnt vmcnt(0)" ::: "memory"); __hip_atomic_store(flag, MAGIC, __ATOMIC_RELEASE, __HIP_MEMORY_SCOPE_AGENT); }
;         } else if (threadIdx.x == 0) {
;             unsigned sp = 0; while (__hip_atomic_load(flag, __ATOMIC_RELAXED, __HIP_MEMORY_SCOPE_AGENT) != MAGIC) { __builtin_amdgcn_s_sleep(1); if (++sp > (1u << 22)) break; }
;             __builtin_amdgcn_fence(__ATOMIC_ACQUIRE, "agent");
;         }
.LBB0_62:
	v_cmp_eq_u32_e32 vcc, 0, v152
	s_and_saveexec_b64 s[4:5], vcc
	s_cbranch_execz .Linit_done
	s_cmp_lg_u32 s86, 0
	s_cbranch_scc0 .Linit_post
	v_mov_b32_e32 v0, 0
	s_mov_b32 s3, 0x600df1a6
	s_mov_b32 s2, 0x400001
.Linit_spin:
	global_load_dword v1, v0, s[26:27] sc1
	s_waitcnt vmcnt(0)
	v_cmp_eq_u32_e32 vcc, s3, v1
	s_cbranch_vccnz .Linit_acq
	s_sleep 1
	s_add_i32 s2, s2, -1
	s_cmp_eq_u32 s2, 0
	s_cbranch_scc0 .Linit_spin

; #define LAS __attribute__((address_space(3)))
; __device__ __forceinline__ unsigned xb_add(unsigned* p, unsigned v) { return __hip_atomic_fetch_add(p, v, __ATOMIC_RELAXED, __HIP_MEMORY_SCOPE_AGENT); }
; __device__ __forceinline__ unsigned xb_xcc_id() { return (unsigned)__builtin_amdgcn_s_getreg((3 << 11) | 20) & 0xFu; }
; __device__ __forceinline__ XcdBarrier xcd_barrier_post(unsigned* bar, volatile LAS unsigned* st) {
;     XcdBarrier b; b.bar = bar; b.x = xb_xcc_id(); b.st = st;
;     if (threadIdx.x == 0) (void)xb_add(&bar[XB_XCNT(b.x)], 1u);
;     return b;
; }
; __device__ __forceinline__ void xcd_barrier(const XcdBarrier& b) {
;     asm volatile("s_waitcnt vmcnt(0)" ::: "memory");
;     __syncthreads();
;     if (threadIdx.x == 0) {
;         unsigned* bar = b.bar;
;         __builtin_amdgcn_s_waitcnt(0);
;         unsigned nloc = b.st[0], nx = b.st[1];
;         if (nloc == 0u) { xcd_barrier_complete(bar, b.x, nloc, nx); b.st[0] = nloc; b.st[1] = nx; }
;         const unsigned old = xb_add(&bar[XB_XSUB(b.x)], 1u);
.Linit_post:
	v_readlane_b32 s2, v255, 1
	s_nop 3
	s_lshl_b32 s2, s2, 8
	v_mov_b32_e32 v0, s2
	v_mov_b32_e32 v1, 1
	global_atomic_add v0, v1, s[96:97] offset:1024
.Linit_done:
	s_or_b64 exec, exec, s[4:5]
	s_waitcnt vmcnt(0)
	s_waitcnt lgkmcnt(0)
	s_barrier
	s_mov_b64 s[0:1], exec
	v_readlane_b32 s2, v255, 2
	v_readlane_b32 s3, v255, 3
	s_and_b64 s[2:3], s[0:1], s[2:3]
	s_mov_b64 exec, s[2:3]
	s_cbranch_execz .LBB0_115
	s_add_i32 s2, 0, 0x20000
	v_mov_b32_e32 v0, s2
	s_waitcnt vmcnt(0) expcnt(0) lgkmcnt(0)
	ds_read_b32 v2, v0
	s_add_i32 s2, 0, 0x20004
	v_mov_b32_e32 v0, s2
	ds_read_b32 v0, v0
	s_waitcnt lgkmcnt(1)
	v_cmp_ne_u32_e32 vcc, 0, v2
	s_cbranch_vccnz .LBB0_79
	s_add_u32 s4, s72, 0x580200
	s_addc_u32 s5, s73, 0
	s_add_u32 s6, s72, 0x580400
	s_addc_u32 s7, s73, 0
	s_add_u32 s8, s72, 0x580500
	s_addc_u32 s9, s73, 0
	s_add_u32 s10, s72, 0x580600
	s_addc_u32 s11, s73, 0
	s_add_u32 s12, s72, 0x580700
	s_addc_u32 s13, s73, 0
	s_add_u32 s14, s72, 0x580800
	s_addc_u32 s15, s73, 0
	s_add_u32 s28, s72, 0x580900
	s_addc_u32 s29, s73, 0
	s_add_u32 s30, s72, 0x580a00
	s_addc_u32 s31, s73, 0
	s_add_u32 s34, s72, 0x580b00
	s_addc_u32 s35, s73, 0
	s_add_u32 s36, s72, 0x580c00
	s_addc_u32 s37, s73, 0
	s_add_u32 s38, s72, 0x580d00
	s_addc_u32 s39, s73, 0
	s_add_u32 s40, s72, 0x580e00
	s_addc_u32 s41, s73, 0
	s_add_u32 s42, s72, 0x580f00
	s_addc_u32 s43, s73, 0
	s_add_u32 s44, s72, 0x581000
	s_addc_u32 s45, s73, 0
	s_add_u32 s46, s72, 0x581100
	s_addc_u32 s47, s73, 0
	s_add_u32 s76, s72, 0x581200
	v_readlane_b32 s2, v255, 0
	s_addc_u32 s77, s73, 0
	s_mul_i32 s2, s75, s2
	s_add_u32 s78, s72, 0x581300
	s_mul_i32 s2, s2, s74
	s_addc_u32 s79, s73, 0
	s_mov_b32 s3, 1
	v_mov_b32_e32 v16, 0
	s_branch .LBB0_66
